# GEMM prologue of the residual-initialised phases (P2, P7, P9) also issues the K-tile 1 loads before the first wait
# baseline (speedup 1.0000x reference)
.LBB0_409:
	s_mov_b64 s[58:59], 0x80
	s_add_i32 m0, s75, 0x18000
	v_lshl_add_u64 v[216:217], v[98:99], 0, s[58:59]
	global_load_lds_dwordx4 v[216:217], off
	s_add_i32 m0, s75, 0x1a000
	s_add_u32 s96, s64, 0x8000
	v_lshl_add_u64 v[216:217], v[96:97], 0, s[58:59]
	s_addc_u32 s97, s65, 0
	s_add_i32 s94, s75, 0x8000
	global_load_lds_dwordx4 v[216:217], off
	v_lshl_add_u64 v[216:217], s[96:97], 0, v[128:129]
	s_mov_b32 m0, s94
	s_add_i32 s95, s75, 0xa000
	global_load_lds_dwordx4 v[216:217], off
	v_lshl_add_u64 v[216:217], s[96:97], 0, v[132:133]
	s_add_u32 s96, s8, 0xb0080
	s_mov_b32 m0, s95
	s_addc_u32 s97, s9, 0
	global_load_lds_dwordx4 v[216:217], off
	s_add_i32 m0, s75, 0x1c000
	v_lshl_add_u64 v[216:217], s[96:97], 0, v[130:131]
	global_load_lds_dwordx4 v[216:217], off
	v_lshl_add_u64 v[216:217], s[96:97], 0, v[134:135]
	s_add_i32 m0, s75, 0x1e000
	s_nop 0
	global_load_lds_dwordx4 v[216:217], off
	s_waitcnt vmcnt(6)
	v_lshlrev_b32_e32 v88, 16, v40
	v_and_b32_e32 v89, 0xffff0000, v40
	v_lshlrev_b32_e32 v92, 16, v41
	v_and_b32_e32 v93, 0xffff0000, v41
	v_lshlrev_b32_e32 v90, 16, v42
	v_and_b32_e32 v91, 0xffff0000, v42
	v_lshlrev_b32_e32 v94, 16, v43
	v_and_b32_e32 v95, 0xffff0000, v43
	v_lshlrev_b32_e32 v144, 16, v28
	v_and_b32_e32 v145, 0xffff0000, v28
	v_lshlrev_b32_e32 v150, 16, v29
	v_and_b32_e32 v151, 0xffff0000, v29
	v_lshlrev_b32_e32 v146, 16, v30
	v_and_b32_e32 v147, 0xffff0000, v30
	v_lshlrev_b32_e32 v152, 16, v31
	v_and_b32_e32 v153, 0xffff0000, v31
	v_lshlrev_b32_e32 v28, 16, v20
	v_and_b32_e32 v29, 0xffff0000, v20
	v_lshlrev_b32_e32 v40, 16, v21
	v_and_b32_e32 v41, 0xffff0000, v21
	v_lshlrev_b32_e32 v30, 16, v22
	v_and_b32_e32 v31, 0xffff0000, v22
	v_lshlrev_b32_e32 v42, 16, v23
	v_and_b32_e32 v43, 0xffff0000, v23
	v_lshlrev_b32_e32 v20, 16, v26
	v_and_b32_e32 v21, 0xffff0000, v26
	v_lshlrev_b32_e32 v22, 16, v27
	v_and_b32_e32 v23, 0xffff0000, v27
	s_add_i32 m0, s75, 0x18000
	v_lshl_add_u64 v[26:27], v[98:99], 0, s[58:59]
	s_lshl_b32 s7, s4, 13
	s_lshl_b32 s18, s0, 7
	s_barrier
	s_add_i32 m0, s75, 0x1a000
	s_add_u32 s4, s64, 0x8000
	v_lshl_add_u64 v[26:27], v[96:97], 0, s[58:59]
	s_addc_u32 s5, s65, 0
	s_add_i32 s80, s75, 0x8000
	v_lshl_add_u64 v[26:27], s[4:5], 0, v[128:129]
	s_mov_b32 m0, s80
	s_add_i32 s81, s75, 0xa000
	v_lshl_add_u64 v[26:27], s[4:5], 0, v[132:133]
	s_add_u32 s4, s8, 0xb0080
	s_mov_b32 m0, s81
	s_addc_u32 s5, s9, 0
	s_add_i32 m0, s75, 0x1c000
	v_lshl_add_u64 v[26:27], s[4:5], 0, v[130:131]
	v_lshl_add_u64 v[26:27], s[4:5], 0, v[134:135]
	s_add_i32 m0, s75, 0x1e000
	v_or_b32_e32 v182, s1, v108
	v_lshlrev_b32_e32 v156, 16, v24
	v_and_b32_e32 v157, 0xffff0000, v24
	v_lshlrev_b32_e32 v158, 16, v25
	v_and_b32_e32 v159, 0xffff0000, v25
	v_lshlrev_b32_e32 v24, 16, v12
	v_and_b32_e32 v25, 0xffff0000, v12
	v_lshlrev_b32_e32 v160, 16, v13
	v_and_b32_e32 v161, 0xffff0000, v13
	v_lshlrev_b32_e32 v26, 16, v14
	v_and_b32_e32 v27, 0xffff0000, v14
	v_lshlrev_b32_e32 v162, 16, v15
	v_and_b32_e32 v163, 0xffff0000, v15
	v_lshlrev_b32_e32 v12, 16, v4
	v_and_b32_e32 v13, 0xffff0000, v4
	v_lshlrev_b32_e32 v164, 16, v5
	v_and_b32_e32 v165, 0xffff0000, v5
	v_lshlrev_b32_e32 v14, 16, v6
	v_and_b32_e32 v15, 0xffff0000, v6
	v_lshlrev_b32_e32 v166, 16, v7
	v_and_b32_e32 v167, 0xffff0000, v7
	v_lshlrev_b32_e32 v178, 16, v8
	v_and_b32_e32 v179, 0xffff0000, v8
	v_lshlrev_b32_e32 v180, 16, v9
	v_and_b32_e32 v181, 0xffff0000, v9
	v_lshlrev_b32_e32 v4, 16, v10
	v_and_b32_e32 v5, 0xffff0000, v10
	v_lshlrev_b32_e32 v6, 16, v11
	v_and_b32_e32 v7, 0xffff0000, v11
	v_lshlrev_b32_e32 v8, 16, v0
	v_and_b32_e32 v9, 0xffff0000, v0
	v_lshlrev_b32_e32 v10, 16, v1
	v_and_b32_e32 v11, 0xffff0000, v1
	v_lshlrev_b32_e32 v168, 16, v2
	v_and_b32_e32 v169, 0xffff0000, v2
	v_lshlrev_b32_e32 v0, 6, v182
	v_lshlrev_b32_e32 v1, 4, v107
	s_movk_i32 s1, 0x3c0
	v_lshlrev_b32_e32 v2, 2, v182
	v_and_or_b32 v0, v0, s1, v1
	v_and_b32_e32 v2, 32, v2
	v_bitop3_b32 v0, v0, s7, v2 bitop3:0xde
	v_lshlrev_b32_e32 v2, 2, v108
	v_lshl_or_b32 v1, v108, 6, v1
	v_and_b32_e32 v2, 32, v2
	v_bitop3_b32 v183, v1, s18, v2 bitop3:0xde
	v_lshlrev_b32_e32 v1, 10, v100
	v_and_b32_e32 v1, 0xfffff800, v1
	v_lshl_add_u32 v1, v101, 7, v1
	v_and_b32_e32 v2, 1, v100
	v_lshl_or_b32 v1, v2, 6, v1
	v_lshl_add_u32 v136, v102, 1, v1
	v_lshlrev_b32_e32 v1, 10, v103
	v_and_b32_e32 v1, 0xfffff800, v1
	s_waitcnt vmcnt(6)
	v_lshl_add_u32 v1, v104, 7, v1
	v_and_b32_e32 v2, 1, v103
	s_cmpk_lt_u32 s6, 0x100
	v_lshl_or_b32 v1, v2, 6, v1
	v_lshlrev_b32_e32 v70, 16, v60
	v_and_b32_e32 v71, 0xffff0000, v60
	v_lshlrev_b32_e32 v76, 16, v61
	v_and_b32_e32 v77, 0xffff0000, v61
	v_lshlrev_b32_e32 v74, 16, v62
	v_and_b32_e32 v75, 0xffff0000, v62
	v_lshlrev_b32_e32 v78, 16, v63
	v_and_b32_e32 v79, 0xffff0000, v63
	v_lshlrev_b32_e32 v60, 16, v52
	v_and_b32_e32 v61, 0xffff0000, v52
	v_lshlrev_b32_e32 v62, 16, v53
	v_and_b32_e32 v63, 0xffff0000, v53
	v_lshlrev_b32_e32 v52, 16, v54
	v_and_b32_e32 v53, 0xffff0000, v54
	v_lshlrev_b32_e32 v54, 16, v55
	v_and_b32_e32 v55, 0xffff0000, v55
	v_lshlrev_b32_e32 v80, 16, v56
	v_and_b32_e32 v81, 0xffff0000, v56
	v_lshlrev_b32_e32 v82, 16, v57
	v_and_b32_e32 v83, 0xffff0000, v57
	v_lshlrev_b32_e32 v56, 16, v58
	v_and_b32_e32 v57, 0xffff0000, v58
	v_lshlrev_b32_e32 v58, 16, v59
	v_and_b32_e32 v59, 0xffff0000, v59
	v_lshlrev_b32_e32 v64, 16, v44
	v_and_b32_e32 v65, 0xffff0000, v44
	v_lshlrev_b32_e32 v66, 16, v45
	v_and_b32_e32 v67, 0xffff0000, v45
	v_lshlrev_b32_e32 v44, 16, v46
	v_and_b32_e32 v45, 0xffff0000, v46
	v_lshlrev_b32_e32 v46, 16, v47
	v_and_b32_e32 v47, 0xffff0000, v47
	v_lshlrev_b32_e32 v84, 16, v48
	v_and_b32_e32 v85, 0xffff0000, v48
	v_lshlrev_b32_e32 v86, 16, v49
	v_and_b32_e32 v87, 0xffff0000, v49
	v_lshlrev_b32_e32 v48, 16, v50
	v_and_b32_e32 v49, 0xffff0000, v50
	v_lshlrev_b32_e32 v50, 16, v51
	v_and_b32_e32 v51, 0xffff0000, v51
	v_lshlrev_b32_e32 v68, 16, v36
	v_and_b32_e32 v69, 0xffff0000, v36
	v_lshlrev_b32_e32 v72, 16, v37
	v_and_b32_e32 v73, 0xffff0000, v37
	v_lshlrev_b32_e32 v36, 16, v38
	v_and_b32_e32 v37, 0xffff0000, v38
	v_lshlrev_b32_e32 v38, 16, v39
	v_and_b32_e32 v39, 0xffff0000, v39
	v_lshlrev_b32_e32 v148, 16, v32
	v_and_b32_e32 v149, 0xffff0000, v32
	v_lshlrev_b32_e32 v154, 16, v33
	v_and_b32_e32 v155, 0xffff0000, v33
	v_lshlrev_b32_e32 v32, 16, v34
	v_and_b32_e32 v33, 0xffff0000, v34
	v_lshlrev_b32_e32 v34, 16, v35
	v_and_b32_e32 v35, 0xffff0000, v35
	v_lshlrev_b32_e32 v172, 16, v16
	v_and_b32_e32 v173, 0xffff0000, v16
	v_lshlrev_b32_e32 v16, 16, v17
	v_and_b32_e32 v17, 0xffff0000, v17
	v_lshlrev_b32_e32 v174, 16, v18
	v_and_b32_e32 v175, 0xffff0000, v18
	v_lshlrev_b32_e32 v176, 16, v19
	v_and_b32_e32 v177, 0xffff0000, v19
	v_lshlrev_b32_e32 v170, 16, v3
	v_and_b32_e32 v171, 0xffff0000, v3
	s_cselect_b64 s[60:61], -1, 0
	v_cmp_eq_u32_e64 s[4:5], 0, v107
	s_ashr_i32 s82, s30, 31
	s_mov_b32 s83, s30
	s_ashr_i32 s84, s2, 31
	v_or_b32_e32 v184, s0, v106
	v_mov_b32_e32 v137, v131
	v_lshl_add_u32 v138, v105, 1, v1
	v_mov_b32_e32 v139, v131
	s_add_i32 s85, 0, 0x10000
	s_add_i32 s86, 0, 0x14000
	v_add_u32_e32 v185, 0, v0
	v_mov_b64_e32 v[140:141], 0x100
	v_mov_b64_e32 v[142:143], 0xff
	v_mbcnt_hi_u32_b32 v186, -1, v248
	s_barrier
	s_branch .LBB0_412

.LBB0_1243:
	s_mov_b64 s[38:39], 0x80
	s_add_i32 m0, s49, 0x18000
	v_lshl_add_u64 v[216:217], v[136:137], 0, s[38:39]
	global_load_lds_dwordx4 v[216:217], off
	v_lshl_add_u64 v[216:217], v[78:79], 0, s[38:39]
	s_add_i32 m0, s49, 0x1a000
	s_add_i32 s94, s49, 0x8000
	s_add_i32 s95, s49, 0xa000
	global_load_lds_dwordx4 v[216:217], off
	v_lshl_add_u64 v[216:217], v[28:29], 0, s[38:39]
	s_mov_b32 m0, s94
	s_add_u32 s96, s58, 0x40080
	global_load_lds_dwordx4 v[216:217], off
	v_lshl_add_u64 v[216:217], v[76:77], 0, s[38:39]
	s_mov_b32 m0, s95
	s_addc_u32 s97, s59, 0
	global_load_lds_dwordx4 v[216:217], off
	s_add_i32 m0, s49, 0x1c000
	v_lshl_add_u64 v[216:217], s[96:97], 0, v[130:131]
	global_load_lds_dwordx4 v[216:217], off
	v_lshl_add_u64 v[216:217], s[96:97], 0, v[134:135]
	s_add_i32 m0, s49, 0x1e000
	s_nop 0
	global_load_lds_dwordx4 v[216:217], off
	s_waitcnt vmcnt(6)
	v_lshlrev_b32_e32 v124, 16, v64
	v_and_b32_e32 v125, 0xffff0000, v64
	v_lshlrev_b32_e32 v126, 16, v65
	v_and_b32_e32 v127, 0xffff0000, v65
	v_lshlrev_b32_e32 v64, 16, v24
	v_and_b32_e32 v65, 0xffff0000, v24
	v_lshlrev_b32_e32 v66, 16, v25
	v_and_b32_e32 v67, 0xffff0000, v25
	v_lshlrev_b32_e32 v72, 16, v26
	v_and_b32_e32 v73, 0xffff0000, v26
	v_lshlrev_b32_e32 v74, 16, v27
	v_and_b32_e32 v75, 0xffff0000, v27
	v_lshlrev_b32_e32 v24, 16, v22
	v_and_b32_e32 v25, 0xffff0000, v22
	v_lshlrev_b32_e32 v26, 16, v23
	v_and_b32_e32 v27, 0xffff0000, v23
	s_add_i32 m0, s49, 0x18000
	v_lshl_add_u64 v[22:23], v[136:137], 0, s[38:39]
	s_lshl_b32 s7, s7, 13
	s_lshl_b32 s34, s6, 7
	s_barrier
	v_lshl_add_u64 v[22:23], v[78:79], 0, s[38:39]
	s_add_i32 m0, s49, 0x1a000
	s_add_i32 s67, s49, 0x8000
	s_add_i32 s68, s49, 0xa000
	v_lshl_add_u64 v[22:23], v[28:29], 0, s[38:39]
	s_mov_b32 m0, s67
	s_add_u32 s18, s58, 0x40080
	v_lshl_add_u64 v[22:23], v[76:77], 0, s[38:39]
	s_mov_b32 m0, s68
	s_addc_u32 s19, s59, 0
	s_add_i32 m0, s49, 0x1c000
	v_lshl_add_u64 v[22:23], s[18:19], 0, v[130:131]
	v_lshl_add_u64 v[22:23], s[18:19], 0, v[134:135]
	s_add_i32 m0, s49, 0x1e000
	v_or_b32_e32 v148, s5, v146
	v_lshlrev_b32_e32 v136, 6, v148
	v_lshlrev_b32_e32 v137, 4, v145
	s_movk_i32 s5, 0x3c0
	v_lshlrev_b32_e32 v147, 2, v148
	v_and_or_b32 v136, v136, s5, v137
	v_and_b32_e32 v147, 32, v147
	v_bitop3_b32 v147, v136, s7, v147 bitop3:0xde
	v_lshl_or_b32 v136, v146, 6, v137
	v_lshlrev_b32_e32 v137, 2, v146
	v_and_b32_e32 v137, 32, v137
	v_bitop3_b32 v149, v136, s34, v137 bitop3:0xde
	v_lshlrev_b32_e32 v136, 14, v138
	v_and_b32_e32 v137, 1, v138
	v_lshlrev_b32_e32 v138, 14, v141
	v_and_b32_e32 v136, 0xffff8000, v136
	v_and_b32_e32 v138, 0xffff8000, v138
	s_waitcnt vmcnt(6)
	v_lshl_add_u32 v136, v139, 11, v136
	v_lshl_add_u32 v138, v142, 11, v138
	v_and_b32_e32 v139, 1, v141
	s_cmpk_lt_u32 s4, 0x100
	v_lshl_or_b32 v136, v137, 6, v136
	v_lshl_or_b32 v138, v139, 6, v138
	v_lshlrev_b32_e32 v116, 16, v62
	v_and_b32_e32 v117, 0xffff0000, v62
	v_lshlrev_b32_e32 v118, 16, v63
	v_and_b32_e32 v119, 0xffff0000, v63
	v_lshlrev_b32_e32 v112, 16, v54
	v_and_b32_e32 v113, 0xffff0000, v54
	v_lshlrev_b32_e32 v114, 16, v55
	v_and_b32_e32 v115, 0xffff0000, v55
	v_lshlrev_b32_e32 v120, 16, v56
	v_and_b32_e32 v121, 0xffff0000, v56
	v_lshlrev_b32_e32 v122, 16, v57
	v_and_b32_e32 v123, 0xffff0000, v57
	v_lshlrev_b32_e32 v96, 16, v58
	v_and_b32_e32 v97, 0xffff0000, v58
	v_lshlrev_b32_e32 v98, 16, v59
	v_and_b32_e32 v99, 0xffff0000, v59
	v_lshlrev_b32_e32 v104, 16, v60
	v_and_b32_e32 v105, 0xffff0000, v60
	v_lshlrev_b32_e32 v106, 16, v61
	v_and_b32_e32 v107, 0xffff0000, v61
	v_lshlrev_b32_e32 v100, 16, v46
	v_and_b32_e32 v101, 0xffff0000, v46
	v_lshlrev_b32_e32 v102, 16, v47
	v_and_b32_e32 v103, 0xffff0000, v47
	v_lshlrev_b32_e32 v108, 16, v48
	v_and_b32_e32 v109, 0xffff0000, v48
	v_lshlrev_b32_e32 v110, 16, v49
	v_and_b32_e32 v111, 0xffff0000, v49
	v_lshlrev_b32_e32 v80, 16, v50
	v_and_b32_e32 v81, 0xffff0000, v50
	v_lshlrev_b32_e32 v82, 16, v51
	v_and_b32_e32 v83, 0xffff0000, v51
	v_lshlrev_b32_e32 v88, 16, v52
	v_and_b32_e32 v89, 0xffff0000, v52
	v_lshlrev_b32_e32 v90, 16, v53
	v_and_b32_e32 v91, 0xffff0000, v53
	v_lshlrev_b32_e32 v84, 16, v38
	v_and_b32_e32 v85, 0xffff0000, v38
	v_lshlrev_b32_e32 v86, 16, v39
	v_and_b32_e32 v87, 0xffff0000, v39
	v_lshlrev_b32_e32 v92, 16, v40
	v_and_b32_e32 v93, 0xffff0000, v40
	v_lshlrev_b32_e32 v94, 16, v41
	v_and_b32_e32 v95, 0xffff0000, v41
	v_lshlrev_b32_e32 v56, 16, v42
	v_and_b32_e32 v57, 0xffff0000, v42
	v_lshlrev_b32_e32 v58, 16, v43
	v_and_b32_e32 v59, 0xffff0000, v43
	v_lshlrev_b32_e32 v68, 16, v44
	v_and_b32_e32 v69, 0xffff0000, v44
	v_lshlrev_b32_e32 v70, 16, v45
	v_and_b32_e32 v71, 0xffff0000, v45
	v_lshlrev_b32_e32 v44, 16, v34
	v_and_b32_e32 v45, 0xffff0000, v34
	v_lshlrev_b32_e32 v46, 16, v35
	v_and_b32_e32 v47, 0xffff0000, v35
	v_lshlrev_b32_e32 v52, 16, v36
	v_and_b32_e32 v53, 0xffff0000, v36
	v_lshlrev_b32_e32 v54, 16, v37
	v_and_b32_e32 v55, 0xffff0000, v37
	v_lshlrev_b32_e32 v48, 16, v16
	v_and_b32_e32 v49, 0xffff0000, v16
	v_lshlrev_b32_e32 v50, 16, v17
	v_and_b32_e32 v51, 0xffff0000, v17
	v_lshlrev_b32_e32 v60, 16, v18
	v_and_b32_e32 v61, 0xffff0000, v18
	v_lshlrev_b32_e32 v62, 16, v19
	v_and_b32_e32 v63, 0xffff0000, v19
	v_lshlrev_b32_e32 v16, 16, v20
	v_and_b32_e32 v17, 0xffff0000, v20
	v_lshlrev_b32_e32 v18, 16, v21
	v_and_b32_e32 v19, 0xffff0000, v21
	v_lshlrev_b32_e32 v20, 16, v8
	v_and_b32_e32 v21, 0xffff0000, v8
	v_lshlrev_b32_e32 v22, 16, v9
	v_and_b32_e32 v23, 0xffff0000, v9
	v_lshlrev_b32_e32 v76, 16, v10
	v_and_b32_e32 v77, 0xffff0000, v10
	v_lshlrev_b32_e32 v78, 16, v11
	v_and_b32_e32 v79, 0xffff0000, v11
	v_lshlrev_b32_e32 v28, 16, v30
	v_and_b32_e32 v29, 0xffff0000, v30
	v_lshlrev_b32_e32 v30, 16, v31
	v_and_b32_e32 v31, 0xffff0000, v31
	v_lshlrev_b32_e32 v36, 16, v32
	v_and_b32_e32 v37, 0xffff0000, v32
	v_lshlrev_b32_e32 v38, 16, v33
	v_and_b32_e32 v39, 0xffff0000, v33
	v_lshlrev_b32_e32 v32, 16, v0
	v_and_b32_e32 v33, 0xffff0000, v0
	v_lshlrev_b32_e32 v34, 16, v1
	v_and_b32_e32 v35, 0xffff0000, v1
	v_lshlrev_b32_e32 v40, 16, v2
	v_and_b32_e32 v41, 0xffff0000, v2
	v_lshlrev_b32_e32 v42, 16, v3
	v_and_b32_e32 v43, 0xffff0000, v3
	v_lshlrev_b32_e32 v0, 16, v4
	v_and_b32_e32 v1, 0xffff0000, v4
	v_lshlrev_b32_e32 v2, 16, v5
	v_and_b32_e32 v3, 0xffff0000, v5
	v_lshlrev_b32_e32 v8, 16, v6
	v_and_b32_e32 v9, 0xffff0000, v6
	v_lshlrev_b32_e32 v10, 16, v7
	v_and_b32_e32 v11, 0xffff0000, v7
	v_lshlrev_b32_e32 v4, 16, v12
	v_and_b32_e32 v5, 0xffff0000, v12
	v_lshlrev_b32_e32 v6, 16, v13
	v_and_b32_e32 v7, 0xffff0000, v13
	v_lshlrev_b32_e32 v12, 16, v14
	v_and_b32_e32 v13, 0xffff0000, v14
	v_lshlrev_b32_e32 v14, 16, v15
	v_and_b32_e32 v15, 0xffff0000, v15
	s_cselect_b64 s[40:41], -1, 0
	v_cmp_eq_u32_e64 s[4:5], 0, v145
	s_ashr_i32 s69, s30, 31
	s_mov_b32 s70, s30
	s_ashr_i32 s71, s2, 31
	v_or_b32_e32 v150, s6, v144
	v_lshl_add_u32 v136, v140, 1, v136
	v_mov_b32_e32 v137, v131
	v_lshl_add_u32 v138, v143, 1, v138
	v_mov_b32_e32 v139, v131
	v_mov_b64_e32 v[140:141], 0x100
	v_mov_b64_e32 v[142:143], 0xff
	s_add_i32 s72, 0, 0x10000
	s_add_i32 s73, 0, 0x14000
	v_add_u32_e32 v151, 0, v147
	v_mbcnt_hi_u32_b32 v152, -1, v248
	s_barrier
	s_branch .LBB0_1246

.LBB0_1402:
	s_add_u32 s34, s28, 0x40000
	s_addc_u32 s35, s29, 0
	s_add_u32 s63, s28, 0x50000
	s_addc_u32 s64, s29, 0
	s_mov_b64 s[28:29], 0x80
	s_add_i32 m0, s58, 0x18000
	v_lshl_add_u64 v[216:217], v[140:141], 0, s[28:29]
	global_load_lds_dwordx4 v[216:217], off
	s_add_i32 m0, s58, 0x1a000
	s_add_u32 s96, s50, 0x8000
	v_lshl_add_u64 v[216:217], v[138:139], 0, s[28:29]
	s_addc_u32 s97, s51, 0
	s_add_i32 s94, s58, 0x8000
	global_load_lds_dwordx4 v[216:217], off
	v_lshl_add_u64 v[216:217], s[96:97], 0, v[144:145]
	s_mov_b32 m0, s94
	s_add_i32 s95, s58, 0xa000
	global_load_lds_dwordx4 v[216:217], off
	v_lshl_add_u64 v[216:217], s[96:97], 0, v[148:149]
	s_add_u32 s96, s48, 0xb0080
	s_mov_b32 m0, s95
	s_addc_u32 s97, s49, 0
	global_load_lds_dwordx4 v[216:217], off
	s_add_i32 m0, s58, 0x1c000
	v_lshl_add_u64 v[216:217], s[96:97], 0, v[146:147]
	global_load_lds_dwordx4 v[216:217], off
	v_lshl_add_u64 v[216:217], s[96:97], 0, v[150:151]
	s_add_i32 m0, s58, 0x1e000
	s_nop 0
	global_load_lds_dwordx4 v[216:217], off
	s_waitcnt vmcnt(6)
	v_lshlrev_b32_e32 v84, 16, v16
	v_and_b32_e32 v85, 0xffff0000, v16
	v_lshlrev_b32_e32 v96, 16, v17
	v_and_b32_e32 v97, 0xffff0000, v17
	v_lshlrev_b32_e32 v86, 16, v18
	v_and_b32_e32 v87, 0xffff0000, v18
	v_lshlrev_b32_e32 v100, 16, v19
	v_and_b32_e32 v101, 0xffff0000, v19
	v_lshlrev_b32_e32 v16, 16, v12
	v_and_b32_e32 v17, 0xffff0000, v12
	v_lshlrev_b32_e32 v18, 16, v13
	v_and_b32_e32 v19, 0xffff0000, v13
	s_add_i32 m0, s58, 0x18000
	v_lshl_add_u64 v[12:13], v[140:141], 0, s[28:29]
	s_lshl_b32 s0, s0, 13
	s_lshl_b32 s8, s5, 7
	s_barrier
	s_add_i32 m0, s58, 0x1a000
	s_add_u32 s6, s50, 0x8000
	v_lshl_add_u64 v[12:13], v[138:139], 0, s[28:29]
	s_addc_u32 s7, s51, 0
	s_add_i32 s65, s58, 0x8000
	v_lshl_add_u64 v[12:13], s[6:7], 0, v[144:145]
	s_mov_b32 m0, s65
	s_add_i32 s66, s58, 0xa000
	v_lshl_add_u64 v[12:13], s[6:7], 0, v[148:149]
	s_add_u32 s6, s48, 0xb0080
	s_mov_b32 m0, s66
	s_addc_u32 s7, s49, 0
	s_add_i32 m0, s58, 0x1c000
	v_lshl_add_u64 v[12:13], s[6:7], 0, v[146:147]
	v_lshl_add_u64 v[12:13], s[6:7], 0, v[150:151]
	s_add_i32 m0, s58, 0x1e000
	v_or_b32_e32 v178, s1, v179
	v_lshlrev_b32_e32 v162, 16, v0
	v_and_b32_e32 v163, 0xffff0000, v0
	v_lshlrev_b32_e32 v166, 16, v1
	v_and_b32_e32 v167, 0xffff0000, v1
	v_lshlrev_b32_e32 v164, 16, v2
	v_and_b32_e32 v165, 0xffff0000, v2
	v_lshlrev_b32_e32 v0, 6, v178
	v_lshlrev_b32_e32 v1, 4, v159
	s_movk_i32 s1, 0x3c0
	v_lshlrev_b32_e32 v2, 2, v178
	v_and_or_b32 v0, v0, s1, v1
	v_and_b32_e32 v2, 32, v2
	v_bitop3_b32 v0, v0, s0, v2 bitop3:0xde
	v_lshlrev_b32_e32 v2, 2, v179
	v_lshl_or_b32 v1, v179, 6, v1
	v_and_b32_e32 v2, 32, v2
	v_bitop3_b32 v179, v1, s8, v2 bitop3:0xde
	v_and_b32_e32 v1, 63, v230
	v_cmp_eq_u32_e64 s[8:9], 0, v1
	v_lshlrev_b32_e32 v1, 10, v152
	v_and_b32_e32 v1, 0xfffff800, v1
	v_lshl_add_u32 v1, v153, 7, v1
	v_and_b32_e32 v2, 1, v152
	v_lshl_or_b32 v1, v2, 6, v1
	v_lshl_add_u32 v152, v154, 1, v1
	v_lshlrev_b32_e32 v1, 10, v155
	v_and_b32_e32 v1, 0xfffff800, v1
	s_waitcnt vmcnt(6)
	v_lshl_add_u32 v1, v156, 7, v1
	v_and_b32_e32 v2, 1, v155
	s_cmpk_lt_u32 s4, 0x100
	v_lshl_or_b32 v1, v2, 6, v1
	v_lshlrev_b32_e32 v76, 16, v60
	v_and_b32_e32 v77, 0xffff0000, v60
	v_lshlrev_b32_e32 v90, 16, v61
	v_and_b32_e32 v91, 0xffff0000, v61
	v_lshlrev_b32_e32 v88, 16, v62
	v_and_b32_e32 v89, 0xffff0000, v62
	v_lshlrev_b32_e32 v94, 16, v63
	v_and_b32_e32 v95, 0xffff0000, v63
	v_lshlrev_b32_e32 v60, 16, v52
	v_and_b32_e32 v61, 0xffff0000, v52
	v_lshlrev_b32_e32 v64, 16, v53
	v_and_b32_e32 v65, 0xffff0000, v53
	v_lshlrev_b32_e32 v62, 16, v54
	v_and_b32_e32 v63, 0xffff0000, v54
	v_lshlrev_b32_e32 v66, 16, v55
	v_and_b32_e32 v67, 0xffff0000, v55
	v_lshlrev_b32_e32 v52, 16, v56
	v_and_b32_e32 v53, 0xffff0000, v56
	v_lshlrev_b32_e32 v54, 16, v57
	v_and_b32_e32 v55, 0xffff0000, v57
	v_lshlrev_b32_e32 v104, 16, v58
	v_and_b32_e32 v105, 0xffff0000, v58
	v_lshlrev_b32_e32 v106, 16, v59
	v_and_b32_e32 v107, 0xffff0000, v59
	v_lshlrev_b32_e32 v68, 16, v44
	v_and_b32_e32 v69, 0xffff0000, v44
	v_lshlrev_b32_e32 v72, 16, v45
	v_and_b32_e32 v73, 0xffff0000, v45
	v_lshlrev_b32_e32 v70, 16, v46
	v_and_b32_e32 v71, 0xffff0000, v46
	v_lshlrev_b32_e32 v74, 16, v47
	v_and_b32_e32 v75, 0xffff0000, v47
	v_lshlrev_b32_e32 v108, 16, v48
	v_and_b32_e32 v109, 0xffff0000, v48
	v_lshlrev_b32_e32 v112, 16, v49
	v_and_b32_e32 v113, 0xffff0000, v49
	v_lshlrev_b32_e32 v110, 16, v50
	v_and_b32_e32 v111, 0xffff0000, v50
	v_lshlrev_b32_e32 v114, 16, v51
	v_and_b32_e32 v115, 0xffff0000, v51
	v_lshlrev_b32_e32 v48, 16, v36
	v_and_b32_e32 v49, 0xffff0000, v36
	v_lshlrev_b32_e32 v78, 16, v37
	v_and_b32_e32 v79, 0xffff0000, v37
	v_lshlrev_b32_e32 v50, 16, v38
	v_and_b32_e32 v51, 0xffff0000, v38
	v_lshlrev_b32_e32 v92, 16, v39
	v_and_b32_e32 v93, 0xffff0000, v39
	v_lshlrev_b32_e32 v124, 16, v40
	v_and_b32_e32 v125, 0xffff0000, v40
	v_lshlrev_b32_e32 v134, 16, v41
	v_and_b32_e32 v135, 0xffff0000, v41
	v_lshlrev_b32_e32 v126, 16, v42
	v_and_b32_e32 v127, 0xffff0000, v42
	v_lshlrev_b32_e32 v136, 16, v43
	v_and_b32_e32 v137, 0xffff0000, v43
	v_lshlrev_b32_e32 v40, 16, v28
	v_and_b32_e32 v41, 0xffff0000, v28
	v_lshlrev_b32_e32 v116, 16, v29
	v_and_b32_e32 v117, 0xffff0000, v29
	v_lshlrev_b32_e32 v42, 16, v30
	v_and_b32_e32 v43, 0xffff0000, v30
	v_lshlrev_b32_e32 v118, 16, v31
	v_and_b32_e32 v119, 0xffff0000, v31
	v_lshlrev_b32_e32 v98, 16, v32
	v_and_b32_e32 v99, 0xffff0000, v32
	v_lshlrev_b32_e32 v120, 16, v33
	v_and_b32_e32 v121, 0xffff0000, v33
	v_lshlrev_b32_e32 v102, 16, v34
	v_and_b32_e32 v103, 0xffff0000, v34
	v_lshlrev_b32_e32 v122, 16, v35
	v_and_b32_e32 v123, 0xffff0000, v35
	v_lshlrev_b32_e32 v56, 16, v20
	v_and_b32_e32 v57, 0xffff0000, v20
	v_lshlrev_b32_e32 v80, 16, v21
	v_and_b32_e32 v81, 0xffff0000, v21
	v_lshlrev_b32_e32 v58, 16, v22
	v_and_b32_e32 v59, 0xffff0000, v22
	v_lshlrev_b32_e32 v82, 16, v23
	v_and_b32_e32 v83, 0xffff0000, v23
	v_lshlrev_b32_e32 v128, 16, v24
	v_and_b32_e32 v129, 0xffff0000, v24
	v_lshlrev_b32_e32 v130, 16, v25
	v_and_b32_e32 v131, 0xffff0000, v25
	v_lshlrev_b32_e32 v20, 16, v26
	v_and_b32_e32 v21, 0xffff0000, v26
	v_lshlrev_b32_e32 v22, 16, v27
	v_and_b32_e32 v23, 0xffff0000, v27
	v_lshlrev_b32_e32 v132, 16, v14
	v_and_b32_e32 v133, 0xffff0000, v14
	v_lshlrev_b32_e32 v170, 16, v15
	v_and_b32_e32 v171, 0xffff0000, v15
	v_lshlrev_b32_e32 v138, 16, v4
	v_and_b32_e32 v139, 0xffff0000, v4
	v_lshlrev_b32_e32 v142, 16, v5
	v_and_b32_e32 v143, 0xffff0000, v5
	v_lshlrev_b32_e32 v140, 16, v6
	v_and_b32_e32 v141, 0xffff0000, v6
	v_lshlrev_b32_e32 v160, 16, v7
	v_and_b32_e32 v161, 0xffff0000, v7
	v_lshlrev_b32_e32 v172, 16, v8
	v_and_b32_e32 v173, 0xffff0000, v8
	v_lshlrev_b32_e32 v4, 16, v9
	v_and_b32_e32 v5, 0xffff0000, v9
	v_lshlrev_b32_e32 v174, 16, v10
	v_and_b32_e32 v175, 0xffff0000, v10
	v_lshlrev_b32_e32 v176, 16, v11
	v_and_b32_e32 v177, 0xffff0000, v11
	v_lshlrev_b32_e32 v168, 16, v3
	v_and_b32_e32 v169, 0xffff0000, v3
	s_cselect_b64 s[36:37], -1, 0
	v_cmp_eq_u32_e64 s[0:1], 0, v159
	s_ashr_i32 s67, s30, 31
	s_ashr_i32 s68, s2, 31
	v_or_b32_e32 v180, s5, v158
	v_mov_b32_e32 v153, v147
	v_lshl_add_u32 v154, v157, 1, v1
	v_mov_b32_e32 v155, v147
	s_add_i32 s69, 0, 0x10000
	s_add_i32 s70, 0, 0x14000
	v_add_u32_e32 v181, 0, v0
	v_mbcnt_hi_u32_b32 v182, -1, v248
	v_mov_b32_e32 v183, 0x358637bd
	s_mov_b64 s[38:39], 0x80000
	s_mov_b32 s71, 0x80000
	s_mov_b64 s[40:41], 0x90000
	s_mov_b32 s72, 0x90000
	s_mov_b64 s[42:43], 0xa0000
	s_mov_b32 s73, 0xa0000
	s_mov_b32 s74, 0xb0000
	v_mov_b64_e32 v[156:157], 0x100
	v_mov_b64_e32 v[158:159], 0xff
	s_barrier
	s_branch .LBB0_1405
